# HGRN c3: 12 per-direction staging loads issued up front with counted waits (was 8 serialized round trips)
# speedup vs baseline: 1.0012x; 1.0012x over previous
; DEV void phase_hg_c3(const Params& p, char* smem) {
;     ...
;       __syncthreads();
;       const int k = tid & 127, half = tid >> 7;
;       {
;         const bf16_t* lsrc = (dir ? LBp : LFp);
; #pragma unroll
;         for (int i = 0; i < 4; i++) {
;           int id = tid + i * 256; int s = id >> 4, cc = id & 15;
;           const size_t go = (size_t)(r0 + s) * 1024 + h * 128 + cc * 8;
;           uint4 u = *(const uint4*)(IH + go);
;           *(uint4*)(Kin + s * 144 + cc * 8) = *(const uint4*)(lsrc + go);
;           *(uint4*)(Qin + s * 144 + cc * 8) = *(const uint4*)(QH + go);
;           bf16_t* vt = Vt + (cc * 8) * 80 + s;
;           vt[0] = (bf16_t)(u.x & 0xffff); vt[80] = (bf16_t)(u.x >> 16); vt[160] = (bf16_t)(u.y & 0xffff); vt[240] = (bf16_t)(u.y >> 16);
;           vt[320] = (bf16_t)(u.z & 0xffff); vt[400] = (bf16_t)(u.z >> 16); vt[480] = (bf16_t)(u.w & 0xffff); vt[560] = (bf16_t)(u.w >> 16);
;         }
;       }
;       u32x4 spr[8];
;       {
;         const bf16_t* sp = DS + ((size_t)(bh * 2 + dir) * 132 + hg_step(cidx, dir)) * 16384;
; #pragma unroll
;         for (int i = 0; i < 8; i++) { int id = tid + i * 256; int row = id >> 4, cc = id & 15; spr[i] = *(const u32x4*)(sp + row * 128 + cc * 8); }
;       }
.LBB0_279:
	s_xor_b64 s[78:79], s[6:7], -1
	s_and_b64 s[14:15], s[6:7], exec
	s_mov_b32 s14, 0xe400000
	s_cselect_b32 s14, s14, 0x10500000
	s_add_u32 s14, s28, s14
	s_addc_u32 s15, s29, 0
	s_waitcnt vmcnt(19)
	v_lshl_add_u64 v[38:39], v[84:85], 1, s[14:15]
	v_lshl_add_u64 v[42:43], v[90:91], 1, s[14:15]
	v_lshl_add_u64 v[46:47], v[96:97], 1, s[14:15]
	v_lshl_add_u64 v[50:51], v[102:103], 1, s[14:15]
	s_waitcnt lgkmcnt(0)
	s_barrier
	global_load_dwordx4 v[38:41], v[38:39], off
	global_load_dwordx4 v[34:37], v[86:87], off
	global_load_dwordx4 v[172:175], v[88:89], off
	global_load_dwordx4 v[42:45], v[42:43], off
	global_load_dwordx4 v[176:179], v[92:93], off
	global_load_dwordx4 v[180:183], v[94:95], off
	global_load_dwordx4 v[46:49], v[46:47], off
	global_load_dwordx4 v[184:187], v[98:99], off
	global_load_dwordx4 v[188:191], v[100:101], off
	global_load_dwordx4 v[50:53], v[50:51], off
	global_load_dwordx4 v[236:239], v[104:105], off
	global_load_dwordx4 v[240:243], v[106:107], off
	s_waitcnt vmcnt(11)
	ds_write_b128 v133, v[38:41]
	s_waitcnt vmcnt(10)
	ds_write_b16 v134, v34 offset:36864
	ds_write_b16_d16_hi v134, v34 offset:37024
	ds_write_b16 v134, v35 offset:37184
	ds_write_b16_d16_hi v134, v35 offset:37344
	ds_write_b16 v134, v36 offset:37504
	ds_write_b16_d16_hi v134, v36 offset:37664
	ds_write_b16 v134, v37 offset:37824
	ds_write_b16_d16_hi v134, v37 offset:37984
	s_waitcnt vmcnt(9)
	ds_write_b128 v132, v[172:175]
	s_waitcnt vmcnt(8)
	ds_write_b128 v137, v[42:45]
	s_waitcnt vmcnt(7)
	ds_write_b16 v138, v176 offset:36864
	ds_write_b16_d16_hi v138, v176 offset:37024
	ds_write_b16 v138, v177 offset:37184
	ds_write_b16_d16_hi v138, v177 offset:37344
	ds_write_b16 v138, v178 offset:37504
	ds_write_b16_d16_hi v138, v178 offset:37664
	ds_write_b16 v138, v179 offset:37824
	ds_write_b16_d16_hi v138, v179 offset:37984
	s_waitcnt vmcnt(6)
	ds_write_b128 v136, v[180:183]
	s_waitcnt vmcnt(5)
	ds_write_b128 v141, v[46:49]
	s_waitcnt vmcnt(4)
	ds_write_b16 v142, v184 offset:36864
	ds_write_b16_d16_hi v142, v184 offset:37024
	ds_write_b16 v142, v185 offset:37184
	ds_write_b16_d16_hi v142, v185 offset:37344
	ds_write_b16 v142, v186 offset:37504
	ds_write_b16_d16_hi v142, v186 offset:37664
	ds_write_b16 v142, v187 offset:37824
	ds_write_b16_d16_hi v142, v187 offset:37984
	s_waitcnt vmcnt(3)
	ds_write_b128 v140, v[188:191]
	s_waitcnt vmcnt(2)
	ds_write_b128 v145, v[50:53]
	s_waitcnt vmcnt(1)
	ds_write_b16 v146, v236 offset:36864
	ds_write_b16_d16_hi v146, v236 offset:37024
	ds_write_b16 v146, v237 offset:37184
	ds_write_b16_d16_hi v146, v237 offset:37344
	ds_write_b16 v146, v238 offset:37504
	ds_write_b16_d16_hi v146, v238 offset:37664
	ds_write_b16 v146, v239 offset:37824
	ds_write_b16_d16_hi v146, v239 offset:37984
	s_waitcnt vmcnt(0)
	ds_write_b128 v144, v[240:243]
	v_mov_b32_e32 v0, 0
	s_or_b32 s14, s20, s44
	s_and_b64 s[6:7], s[6:7], exec
	s_cselect_b32 s6, s51, s45
	s_mulk_i32 s14, 0x84
	s_ashr_i32 s7, s6, 31
	s_add_u32 s6, s14, s6
	s_addc_u32 s7, 0, s7
	s_lshl_b64 s[6:7], s[6:7], 15
	v_lshl_add_u64 v[62:63], v[66:67], 0, s[6:7]
	v_lshl_add_u64 v[42:43], v[72:73], 1, v[62:63]
	v_lshl_add_u64 v[46:47], v[74:75], 1, v[62:63]
	v_lshl_add_u64 v[50:51], v[76:77], 1, v[62:63]
	v_lshl_add_u64 v[54:55], v[78:79], 1, v[62:63]
	v_lshl_add_u64 v[58:59], v[80:81], 1, v[62:63]
	s_mov_b32 s6, 0
	v_lshl_add_u64 v[34:35], v[68:69], 1, v[62:63]
	v_lshl_add_u64 v[38:39], v[70:71], 1, v[62:63]
	v_lshl_add_u64 v[62:63], v[82:83], 1, v[62:63]
	global_load_dwordx4 v[34:37], v[34:35], off
	s_nop 0
	global_load_dwordx4 v[38:41], v[38:39], off
	s_nop 0
	global_load_dwordx4 v[42:45], v[42:43], off
	s_nop 0
	global_load_dwordx4 v[46:49], v[46:47], off
	s_nop 0
	global_load_dwordx4 v[50:53], v[50:51], off
	s_nop 0
	global_load_dwordx4 v[54:57], v[54:55], off
	s_nop 0
	global_load_dwordx4 v[58:61], v[58:59], off
	s_nop 0
	global_load_dwordx4 v[62:65], v[62:63], off
	s_waitcnt lgkmcnt(0)
	s_barrier
